# key-head rope: the 10 row loads of a thread's 5 key heads issued up front with counted waits
# speedup vs baseline: 1.0151x; 1.0044x over previous
.LBB0_333:
	v_lshrrev_b32_e32 v58, 7, v26
	v_lshlrev_b32_e32 v58, 12, v58
	v_and_b32_e32 v59, 2, v26
	v_lshlrev_b32_e32 v59, 9, v59
	v_or_b32_e32 v58, v58, v59
	v_and_b32_e32 v59, 1, v26
	v_lshlrev_b32_e32 v59, 4, v59
	v_or_b32_e32 v58, v58, v59
	v_bfe_u32 v59, v26, 2, 5
	v_lshlrev_b32_e32 v59, 5, v59
	v_or_b32_e32 v58, v58, v59
	v_add_co_u32_e32 v60, vcc, v56, v58
	s_nop 1
	v_addc_co_u32_e32 v61, vcc, 0, v57, vcc
	v_ashrrev_i32_e32 v22, 2, v26
	v_ashrrev_i32_e32 v23, 31, v22
	v_lshlrev_b32_e32 v0, 3, v26
	v_and_b32_e32 v24, 24, v0
	v_lshlrev_b64 v[2:3], 8, v[22:23]
	v_lshl_add_u64 v[2:3], v[20:21], 0, v[2:3]
	v_lshlrev_b32_e32 v0, 3, v24
	v_lshl_add_u64 v[14:15], v[2:3], 0, v[0:1]
	global_load_dwordx4 v[2:5], v[14:15], off
	global_load_dwordx4 v[6:9], v[14:15], off offset:16
	global_load_dwordx4 v[10:13], v[14:15], off offset:32
	s_nop 0
	global_load_dwordx4 v[14:17], v[14:15], off offset:48
	v_mad_i64_i32 v[22:23], s[8:9], v22, s61, v[18:19]
	v_lshlrev_b32_e32 v0, 1, v24
	v_lshl_add_u64 v[22:23], v[22:23], 0, v[0:1]
	s_mov_b32 s10, 0
	s_movk_i32 s11, 0x200
	s_movk_i32 s12, 0x100
	s_waitcnt vmcnt(0) lgkmcnt(0)
	v_mov_b32_e32 v24, v15
	v_mov_b32_e32 v25, v17
	v_mov_b32_e32 v15, v16
	v_mov_b32_e32 v16, v11
	v_mov_b32_e32 v17, v13
	v_mov_b32_e32 v11, v12
	v_mov_b32_e32 v12, v7
	v_mov_b32_e32 v13, v9
	v_mov_b32_e32 v7, v8
	v_mov_b32_e32 v8, v3
	v_mov_b32_e32 v9, v5
	v_mov_b32_e32 v3, v4
	s_movk_i32 s74, 0x300
	v_lshl_add_u64 v[104:105], s[74:75], 1, v[22:23]
	global_load_dwordx4 v[64:67], v[104:105], off
	global_load_dwordx4 v[68:71], v[104:105], off offset:64
	s_movk_i32 s74, 0x340
	v_lshl_add_u64 v[106:107], s[74:75], 1, v[22:23]
	global_load_dwordx4 v[72:75], v[106:107], off
	global_load_dwordx4 v[76:79], v[106:107], off offset:64
	s_movk_i32 s74, 0x400
	v_lshl_add_u64 v[108:109], s[74:75], 1, v[22:23]
	global_load_dwordx4 v[80:83], v[108:109], off
	global_load_dwordx4 v[84:87], v[108:109], off offset:64
	s_movk_i32 s74, 0x440
	v_lshl_add_u64 v[110:111], s[74:75], 1, v[22:23]
	global_load_dwordx4 v[88:91], v[110:111], off
	global_load_dwordx4 v[92:95], v[110:111], off offset:64
	s_movk_i32 s74, 0x700
	v_lshl_add_u64 v[112:113], s[74:75], 1, v[22:23]
	global_load_dwordx4 v[96:99], v[112:113], off
	global_load_dwordx4 v[100:103], v[112:113], off offset:64
	s_waitcnt vmcnt(8)
	s_nop 1
	v_mov_b32_e32 v28, v64
	v_mov_b32_e32 v29, v65
	v_mov_b32_e32 v30, v66
	v_mov_b32_e32 v31, v67
	v_mov_b32_e32 v32, v68
	v_mov_b32_e32 v33, v69
	v_mov_b32_e32 v34, v70
	v_mov_b32_e32 v35, v71
	s_movk_i32 s74, 0x300
	s_and_b32 s98, s74, 64
	s_lshl_b32 s98, s98, 16
	v_lshl_add_u64 v[62:63], v[60:61], 0, s[98:99]
	v_lshlrev_b32_e32 v36, 16, v28
	v_lshlrev_b32_e32 v38, 16, v32
	v_and_b32_e32 v39, 0xffff0000, v32
	v_and_b32_e32 v37, 0xffff0000, v28
	v_pk_mul_f32 v[40:41], v[2:3], v[38:39]
	v_pk_mul_f32 v[38:39], v[8:9], v[38:39]
	v_lshlrev_b32_e32 v32, 16, v33
	v_and_b32_e32 v33, 0xffff0000, v33
	v_pk_fma_f32 v[40:41], v[8:9], v[36:37], v[40:41]
	v_pk_fma_f32 v[36:37], v[2:3], v[36:37], v[38:39] neg_lo:[0,0,1] neg_hi:[0,0,1]
	v_lshlrev_b32_e32 v28, 16, v29
	v_and_b32_e32 v29, 0xffff0000, v29
	v_pk_mul_f32 v[38:39], v[6:7], v[32:33]
	v_pk_mul_f32 v[32:33], v[12:13], v[32:33]
	v_lshlrev_b32_e32 v42, 16, v34
	v_and_b32_e32 v43, 0xffff0000, v34
	v_pk_fma_f32 v[38:39], v[12:13], v[28:29], v[38:39]
	v_pk_fma_f32 v[32:33], v[6:7], v[28:29], v[32:33] neg_lo:[0,0,1] neg_hi:[0,0,1]
	v_lshlrev_b32_e32 v28, 16, v30
	v_and_b32_e32 v29, 0xffff0000, v30
	v_pk_mul_f32 v[44:45], v[10:11], v[42:43]
	v_pk_mul_f32 v[42:43], v[16:17], v[42:43]
	v_pk_fma_f32 v[44:45], v[16:17], v[28:29], v[44:45]
	v_pk_fma_f32 v[42:43], v[10:11], v[28:29], v[42:43] neg_lo:[0,0,1] neg_hi:[0,0,1]
	v_lshlrev_b32_e32 v28, 16, v31
	v_and_b32_e32 v29, 0xffff0000, v31
	v_lshlrev_b32_e32 v30, 16, v35
	v_and_b32_e32 v31, 0xffff0000, v35
	v_pk_mul_f32 v[34:35], v[14:15], v[30:31]
	v_pk_mul_f32 v[30:31], v[24:25], v[30:31]
	v_pk_fma_f32 v[34:35], v[24:25], v[28:29], v[34:35]
	v_pk_fma_f32 v[46:47], v[14:15], v[28:29], v[30:31] neg_lo:[0,0,1] neg_hi:[0,0,1]
	v_cvt_pk_bf16_f32 v28, v36, v37
	v_cvt_pk_bf16_f32 v29, v32, v33
	v_cvt_pk_bf16_f32 v30, v42, v43
	v_cvt_pk_bf16_f32 v31, v46, v47
	global_store_dwordx4 v[104:105], v[28:31], off
	global_store_dwordx4 v[62:63], v[28:31], off
	s_nop 1
	v_cvt_pk_bf16_f32 v28, v40, v41
	v_cvt_pk_bf16_f32 v29, v38, v39
	v_cvt_pk_bf16_f32 v30, v44, v45
	v_cvt_pk_bf16_f32 v31, v34, v35
	global_store_dwordx4 v[104:105], v[28:31], off offset:64
	global_store_dwordx4 v[62:63], v[28:31], off offset:2048
	s_waitcnt vmcnt(10)
	s_nop 1
	v_mov_b32_e32 v28, v72
	v_mov_b32_e32 v29, v73
	v_mov_b32_e32 v30, v74
	v_mov_b32_e32 v31, v75
	v_mov_b32_e32 v32, v76
	v_mov_b32_e32 v33, v77
	v_mov_b32_e32 v34, v78
	v_mov_b32_e32 v35, v79
	s_movk_i32 s74, 0x340
	s_and_b32 s98, s74, 64
	s_lshl_b32 s98, s98, 16
	v_lshl_add_u64 v[62:63], v[60:61], 0, s[98:99]
	v_lshlrev_b32_e32 v36, 16, v28
	v_lshlrev_b32_e32 v38, 16, v32
	v_and_b32_e32 v39, 0xffff0000, v32
	v_and_b32_e32 v37, 0xffff0000, v28
	v_pk_mul_f32 v[40:41], v[2:3], v[38:39]
	v_pk_mul_f32 v[38:39], v[8:9], v[38:39]
	v_lshlrev_b32_e32 v32, 16, v33
	v_and_b32_e32 v33, 0xffff0000, v33
	v_pk_fma_f32 v[40:41], v[8:9], v[36:37], v[40:41]
	v_pk_fma_f32 v[36:37], v[2:3], v[36:37], v[38:39] neg_lo:[0,0,1] neg_hi:[0,0,1]
	v_lshlrev_b32_e32 v28, 16, v29
	v_and_b32_e32 v29, 0xffff0000, v29
	v_pk_mul_f32 v[38:39], v[6:7], v[32:33]
	v_pk_mul_f32 v[32:33], v[12:13], v[32:33]
	v_lshlrev_b32_e32 v42, 16, v34
	v_and_b32_e32 v43, 0xffff0000, v34
	v_pk_fma_f32 v[38:39], v[12:13], v[28:29], v[38:39]
	v_pk_fma_f32 v[32:33], v[6:7], v[28:29], v[32:33] neg_lo:[0,0,1] neg_hi:[0,0,1]
	v_lshlrev_b32_e32 v28, 16, v30
	v_and_b32_e32 v29, 0xffff0000, v30
	v_pk_mul_f32 v[44:45], v[10:11], v[42:43]
	v_pk_mul_f32 v[42:43], v[16:17], v[42:43]
	v_pk_fma_f32 v[44:45], v[16:17], v[28:29], v[44:45]
	v_pk_fma_f32 v[42:43], v[10:11], v[28:29], v[42:43] neg_lo:[0,0,1] neg_hi:[0,0,1]
	v_lshlrev_b32_e32 v28, 16, v31
	v_and_b32_e32 v29, 0xffff0000, v31
	v_lshlrev_b32_e32 v30, 16, v35
	v_and_b32_e32 v31, 0xffff0000, v35
	v_pk_mul_f32 v[34:35], v[14:15], v[30:31]
	v_pk_mul_f32 v[30:31], v[24:25], v[30:31]
	v_pk_fma_f32 v[34:35], v[24:25], v[28:29], v[34:35]
	v_pk_fma_f32 v[46:47], v[14:15], v[28:29], v[30:31] neg_lo:[0,0,1] neg_hi:[0,0,1]
	v_cvt_pk_bf16_f32 v28, v36, v37
	v_cvt_pk_bf16_f32 v29, v32, v33
	v_cvt_pk_bf16_f32 v30, v42, v43
	v_cvt_pk_bf16_f32 v31, v46, v47
	global_store_dwordx4 v[106:107], v[28:31], off
	global_store_dwordx4 v[62:63], v[28:31], off
	s_nop 1
	v_cvt_pk_bf16_f32 v28, v40, v41
	v_cvt_pk_bf16_f32 v29, v38, v39
	v_cvt_pk_bf16_f32 v30, v44, v45
	v_cvt_pk_bf16_f32 v31, v34, v35
	global_store_dwordx4 v[106:107], v[28:31], off offset:64
	global_store_dwordx4 v[62:63], v[28:31], off offset:2048
	s_waitcnt vmcnt(12)
	s_nop 1
	v_mov_b32_e32 v28, v80
	v_mov_b32_e32 v29, v81
	v_mov_b32_e32 v30, v82
	v_mov_b32_e32 v31, v83
	v_mov_b32_e32 v32, v84
	v_mov_b32_e32 v33, v85
	v_mov_b32_e32 v34, v86
	v_mov_b32_e32 v35, v87
	v_lshlrev_b32_e32 v36, 16, v28
	v_lshlrev_b32_e32 v38, 16, v32
	v_and_b32_e32 v39, 0xffff0000, v32
	v_and_b32_e32 v37, 0xffff0000, v28
	v_pk_mul_f32 v[40:41], v[2:3], v[38:39]
	v_pk_mul_f32 v[38:39], v[8:9], v[38:39]
	v_lshlrev_b32_e32 v32, 16, v33
	v_and_b32_e32 v33, 0xffff0000, v33
	v_pk_fma_f32 v[40:41], v[8:9], v[36:37], v[40:41]
	v_pk_fma_f32 v[36:37], v[2:3], v[36:37], v[38:39] neg_lo:[0,0,1] neg_hi:[0,0,1]
	v_lshlrev_b32_e32 v28, 16, v29
	v_and_b32_e32 v29, 0xffff0000, v29
	v_pk_mul_f32 v[38:39], v[6:7], v[32:33]
	v_pk_mul_f32 v[32:33], v[12:13], v[32:33]
	v_lshlrev_b32_e32 v42, 16, v34
	v_and_b32_e32 v43, 0xffff0000, v34
	v_pk_fma_f32 v[38:39], v[12:13], v[28:29], v[38:39]
	v_pk_fma_f32 v[32:33], v[6:7], v[28:29], v[32:33] neg_lo:[0,0,1] neg_hi:[0,0,1]
	v_lshlrev_b32_e32 v28, 16, v30
	v_and_b32_e32 v29, 0xffff0000, v30
	v_pk_mul_f32 v[44:45], v[10:11], v[42:43]
	v_pk_mul_f32 v[42:43], v[16:17], v[42:43]
	v_pk_fma_f32 v[44:45], v[16:17], v[28:29], v[44:45]
	v_pk_fma_f32 v[42:43], v[10:11], v[28:29], v[42:43] neg_lo:[0,0,1] neg_hi:[0,0,1]
	v_lshlrev_b32_e32 v28, 16, v31
	v_and_b32_e32 v29, 0xffff0000, v31
	v_lshlrev_b32_e32 v30, 16, v35
	v_and_b32_e32 v31, 0xffff0000, v35
	v_pk_mul_f32 v[34:35], v[14:15], v[30:31]
	v_pk_mul_f32 v[30:31], v[24:25], v[30:31]
	v_pk_fma_f32 v[34:35], v[24:25], v[28:29], v[34:35]
	v_pk_fma_f32 v[46:47], v[14:15], v[28:29], v[30:31] neg_lo:[0,0,1] neg_hi:[0,0,1]
	v_cvt_pk_bf16_f32 v28, v36, v37
	v_cvt_pk_bf16_f32 v29, v32, v33
	v_cvt_pk_bf16_f32 v30, v42, v43
	v_cvt_pk_bf16_f32 v31, v46, v47
	global_store_dwordx4 v[108:109], v[28:31], off
	s_nop 1
	v_cvt_pk_bf16_f32 v28, v40, v41
	v_cvt_pk_bf16_f32 v29, v38, v39
	v_cvt_pk_bf16_f32 v30, v44, v45
	v_cvt_pk_bf16_f32 v31, v34, v35
	global_store_dwordx4 v[108:109], v[28:31], off offset:64
	s_waitcnt vmcnt(12)
	s_nop 1
	v_mov_b32_e32 v28, v88
	v_mov_b32_e32 v29, v89
	v_mov_b32_e32 v30, v90
	v_mov_b32_e32 v31, v91
	v_mov_b32_e32 v32, v92
	v_mov_b32_e32 v33, v93
	v_mov_b32_e32 v34, v94
	v_mov_b32_e32 v35, v95
	v_lshlrev_b32_e32 v36, 16, v28
	v_lshlrev_b32_e32 v38, 16, v32
	v_and_b32_e32 v39, 0xffff0000, v32
	v_and_b32_e32 v37, 0xffff0000, v28
	v_pk_mul_f32 v[40:41], v[2:3], v[38:39]
	v_pk_mul_f32 v[38:39], v[8:9], v[38:39]
	v_lshlrev_b32_e32 v32, 16, v33
	v_and_b32_e32 v33, 0xffff0000, v33
	v_pk_fma_f32 v[40:41], v[8:9], v[36:37], v[40:41]
	v_pk_fma_f32 v[36:37], v[2:3], v[36:37], v[38:39] neg_lo:[0,0,1] neg_hi:[0,0,1]
	v_lshlrev_b32_e32 v28, 16, v29
	v_and_b32_e32 v29, 0xffff0000, v29
	v_pk_mul_f32 v[38:39], v[6:7], v[32:33]
	v_pk_mul_f32 v[32:33], v[12:13], v[32:33]
	v_lshlrev_b32_e32 v42, 16, v34
	v_and_b32_e32 v43, 0xffff0000, v34
	v_pk_fma_f32 v[38:39], v[12:13], v[28:29], v[38:39]
	v_pk_fma_f32 v[32:33], v[6:7], v[28:29], v[32:33] neg_lo:[0,0,1] neg_hi:[0,0,1]
	v_lshlrev_b32_e32 v28, 16, v30
	v_and_b32_e32 v29, 0xffff0000, v30
	v_pk_mul_f32 v[44:45], v[10:11], v[42:43]
	v_pk_mul_f32 v[42:43], v[16:17], v[42:43]
	v_pk_fma_f32 v[44:45], v[16:17], v[28:29], v[44:45]
	v_pk_fma_f32 v[42:43], v[10:11], v[28:29], v[42:43] neg_lo:[0,0,1] neg_hi:[0,0,1]
	v_lshlrev_b32_e32 v28, 16, v31
	v_and_b32_e32 v29, 0xffff0000, v31
	v_lshlrev_b32_e32 v30, 16, v35
	v_and_b32_e32 v31, 0xffff0000, v35
	v_pk_mul_f32 v[34:35], v[14:15], v[30:31]
	v_pk_mul_f32 v[30:31], v[24:25], v[30:31]
	v_pk_fma_f32 v[34:35], v[24:25], v[28:29], v[34:35]
	v_pk_fma_f32 v[46:47], v[14:15], v[28:29], v[30:31] neg_lo:[0,0,1] neg_hi:[0,0,1]
	v_cvt_pk_bf16_f32 v28, v36, v37
	v_cvt_pk_bf16_f32 v29, v32, v33
	v_cvt_pk_bf16_f32 v30, v42, v43
	v_cvt_pk_bf16_f32 v31, v46, v47
	global_store_dwordx4 v[110:111], v[28:31], off
	s_nop 1
	v_cvt_pk_bf16_f32 v28, v40, v41
	v_cvt_pk_bf16_f32 v29, v38, v39
	v_cvt_pk_bf16_f32 v30, v44, v45
	v_cvt_pk_bf16_f32 v31, v34, v35
	global_store_dwordx4 v[110:111], v[28:31], off offset:64
	s_waitcnt vmcnt(12)
	s_nop 1
	v_mov_b32_e32 v28, v96
	v_mov_b32_e32 v29, v97
	v_mov_b32_e32 v30, v98
	v_mov_b32_e32 v31, v99
	v_mov_b32_e32 v32, v100
	v_mov_b32_e32 v33, v101
	v_mov_b32_e32 v34, v102
	v_mov_b32_e32 v35, v103
	v_lshlrev_b32_e32 v36, 16, v28
	v_lshlrev_b32_e32 v38, 16, v32
	v_and_b32_e32 v39, 0xffff0000, v32
	v_and_b32_e32 v37, 0xffff0000, v28
	v_pk_mul_f32 v[40:41], v[2:3], v[38:39]
	v_pk_mul_f32 v[38:39], v[8:9], v[38:39]
	v_lshlrev_b32_e32 v32, 16, v33
	v_and_b32_e32 v33, 0xffff0000, v33
	v_pk_fma_f32 v[40:41], v[8:9], v[36:37], v[40:41]
	v_pk_fma_f32 v[36:37], v[2:3], v[36:37], v[38:39] neg_lo:[0,0,1] neg_hi:[0,0,1]
	v_lshlrev_b32_e32 v28, 16, v29
	v_and_b32_e32 v29, 0xffff0000, v29
	v_pk_mul_f32 v[38:39], v[6:7], v[32:33]
	v_pk_mul_f32 v[32:33], v[12:13], v[32:33]
	v_lshlrev_b32_e32 v42, 16, v34
	v_and_b32_e32 v43, 0xffff0000, v34
	v_pk_fma_f32 v[38:39], v[12:13], v[28:29], v[38:39]
	v_pk_fma_f32 v[32:33], v[6:7], v[28:29], v[32:33] neg_lo:[0,0,1] neg_hi:[0,0,1]
	v_lshlrev_b32_e32 v28, 16, v30
	v_and_b32_e32 v29, 0xffff0000, v30
	v_pk_mul_f32 v[44:45], v[10:11], v[42:43]
	v_pk_mul_f32 v[42:43], v[16:17], v[42:43]
	v_pk_fma_f32 v[44:45], v[16:17], v[28:29], v[44:45]
	v_pk_fma_f32 v[42:43], v[10:11], v[28:29], v[42:43] neg_lo:[0,0,1] neg_hi:[0,0,1]
	v_lshlrev_b32_e32 v28, 16, v31
	v_and_b32_e32 v29, 0xffff0000, v31
	v_lshlrev_b32_e32 v30, 16, v35
	v_and_b32_e32 v31, 0xffff0000, v35
	v_pk_mul_f32 v[34:35], v[14:15], v[30:31]
	v_pk_mul_f32 v[30:31], v[24:25], v[30:31]
	v_pk_fma_f32 v[34:35], v[24:25], v[28:29], v[34:35]
	v_pk_fma_f32 v[46:47], v[14:15], v[28:29], v[30:31] neg_lo:[0,0,1] neg_hi:[0,0,1]
	v_cvt_pk_bf16_f32 v28, v36, v37
	v_cvt_pk_bf16_f32 v29, v32, v33
	v_cvt_pk_bf16_f32 v30, v42, v43
	v_cvt_pk_bf16_f32 v31, v46, v47
	global_store_dwordx4 v[112:113], v[28:31], off
	s_nop 1
	v_cvt_pk_bf16_f32 v28, v40, v41
	v_cvt_pk_bf16_f32 v29, v38, v39
	v_cvt_pk_bf16_f32 v30, v44, v45
	v_cvt_pk_bf16_f32 v31, v34, v35
	global_store_dwordx4 v[112:113], v[28:31], off offset:64
	s_branch .LBB0_332
